# re-measure of the same bytes (chip state check)
# baseline (speedup 1.0000x reference)
.LBB0_6:
	s_load_dwordx4 s[16:19], s[0:1], 0xe0
	s_add_u32 s50, s0, 0xf8
	s_addc_u32 s51, s1, 0
	s_load_dwordx16 s[60:75], s[0:1], 0x0
	v_mov_b32_e32 v191, 0
	s_waitcnt lgkmcnt(0)
	s_add_u32 s4, s18, 0xf595200
	s_addc_u32 s5, s19, 0
	s_add_u32 s22, s18, 0xf595400
	s_addc_u32 s23, s19, 0
	s_add_u32 s38, s18, 0xf595500
	s_addc_u32 s39, s19, 0
	s_add_u32 s30, s18, 0xf595600
	s_addc_u32 s31, s19, 0
	s_add_u32 s24, s18, 0xf595700
	s_addc_u32 s25, s19, 0
	s_add_u32 s26, s18, 0xf595800
	s_addc_u32 s27, s19, 0
	s_add_u32 s28, s18, 0xf595900
	s_addc_u32 s29, s19, 0
	s_add_u32 s12, s18, 0xf595a00
	v_writelane_b32 v250, s4, 6
	s_addc_u32 s13, s19, 0
	v_mov_b32_e32 v238, 0x3727c5ac
	v_writelane_b32 v250, s5, 7
	s_add_u32 s4, s18, 0xf595b00
	s_addc_u32 s5, s19, 0
	v_writelane_b32 v250, s4, 8
	v_mov_b32_e32 v243, 0x2810
	v_mov_b32_e32 v245, 0xd300
	v_writelane_b32 v250, s5, 9
	s_add_u32 s4, s18, 0xf595c00
	s_addc_u32 s5, s19, 0
	v_writelane_b32 v250, s4, 10
	v_mov_b32_e32 v198, 0x3e000000
	v_mov_b32_e32 v242, 0xff800000
	v_writelane_b32 v250, s5, 11
	s_add_u32 s4, s18, 0xf595d00
	s_addc_u32 s5, s19, 0
	v_writelane_b32 v250, s4, 12
	s_mov_b32 s34, 0x800000
	s_movk_i32 s35, 0x4000
	v_writelane_b32 v250, s5, 13
	s_add_u32 s4, s18, 0xf595e00
	s_addc_u32 s5, s19, 0
	v_writelane_b32 v250, s4, 14
	s_movk_i32 s36, 0x90
	s_movk_i32 s33, 0x404
	v_writelane_b32 v250, s5, 15
	s_add_u32 s4, s18, 0xf595f00
	s_addc_u32 s5, s19, 0
	v_writelane_b32 v250, s4, 16
	s_movk_i32 s37, 0x300
	s_movk_i32 s54, 0x2810
	v_writelane_b32 v250, s5, 17
	s_add_u32 s4, s18, 0xf596000
	s_addc_u32 s5, s19, 0
	v_writelane_b32 v250, s4, 18
	s_movk_i32 s55, 0xdff
	s_movk_i32 s57, 0x110
	v_writelane_b32 v250, s5, 19
	s_add_u32 s4, s18, 0xf596100
	s_addc_u32 s5, s19, 0
	v_writelane_b32 v250, s4, 20
	s_mov_b32 s58, 0x2aaaaaab
	s_movk_i32 s59, 0xffd0
	v_writelane_b32 v250, s5, 21
	s_add_u32 s4, s18, 0xf596200
	s_addc_u32 s5, s19, 0
	v_writelane_b32 v250, s4, 22
	s_mov_b32 s76, s20
	s_mov_b32 s97, 0
	s_mov_b32 s98, 1
	v_writelane_b32 v255, s98, 63
	v_writelane_b32 v250, s5, 23
	s_add_u32 s4, s18, 0xf596300
	s_addc_u32 s5, s19, 0
	v_writelane_b32 v250, s4, 24
	s_cmp_eq_u32 s8, 15
	s_mov_b64 s[78:79], 0x80
	v_writelane_b32 v250, s5, 25
	s_cselect_b64 s[4:5], -1, 0
	v_writelane_b32 v250, s4, 26
	s_cmp_eq_u32 s8, 14
	s_nop 0
	v_writelane_b32 v250, s5, 27
	s_cselect_b64 s[4:5], -1, 0
	v_writelane_b32 v250, s4, 28
	s_cmp_eq_u32 s8, 13
	s_nop 0
	v_writelane_b32 v250, s5, 29
	s_cselect_b64 s[4:5], -1, 0
	v_writelane_b32 v250, s4, 30
	s_cmp_eq_u32 s8, 12
	s_nop 0
	v_writelane_b32 v250, s5, 31
	s_cselect_b64 s[4:5], -1, 0
	v_writelane_b32 v250, s4, 32
	s_cmp_eq_u32 s8, 11
	s_nop 0
	v_writelane_b32 v250, s5, 33
	s_cselect_b64 s[4:5], -1, 0
	v_writelane_b32 v250, s4, 34
	s_cmp_eq_u32 s8, 10
	s_nop 0
	v_writelane_b32 v250, s5, 35
	s_cselect_b64 s[4:5], -1, 0
	v_writelane_b32 v250, s4, 36
	s_cmp_eq_u32 s8, 9
	s_nop 0
	v_writelane_b32 v250, s5, 37
	s_cselect_b64 s[4:5], -1, 0
	v_writelane_b32 v250, s4, 38
	s_cmp_eq_u32 s8, 8
	s_nop 0
	v_writelane_b32 v250, s5, 39
	s_cselect_b64 s[4:5], -1, 0
	v_writelane_b32 v250, s4, 40
	s_cmp_eq_u32 s8, 7
	s_nop 0
	v_writelane_b32 v250, s5, 41
	s_cselect_b64 s[4:5], -1, 0
	v_writelane_b32 v250, s4, 42
	s_cmp_eq_u32 s8, 6
	s_nop 0
	v_writelane_b32 v250, s5, 43
	s_cselect_b64 s[4:5], -1, 0
	v_writelane_b32 v250, s4, 44
	s_cmp_eq_u32 s8, 5
	s_nop 0
	v_writelane_b32 v250, s5, 45
	s_cselect_b64 s[4:5], -1, 0
	v_writelane_b32 v250, s4, 46
	s_cmp_eq_u32 s8, 4
	s_nop 0
	v_writelane_b32 v250, s5, 47
	s_cselect_b64 s[4:5], -1, 0
	v_writelane_b32 v250, s4, 48
	s_cmp_eq_u32 s8, 3
	s_nop 0
	v_writelane_b32 v250, s5, 49
	s_cselect_b64 s[4:5], -1, 0
	v_writelane_b32 v250, s4, 50
	s_cmp_eq_u32 s8, 2
	s_nop 0
	v_writelane_b32 v250, s5, 51
	s_cselect_b64 s[4:5], -1, 0
	v_writelane_b32 v250, s4, 52
	s_cmp_eq_u32 s8, 1
	s_nop 0
	v_writelane_b32 v250, s5, 53
	s_cselect_b64 s[4:5], -1, 0
	v_writelane_b32 v250, s4, 54
	s_cmp_eq_u32 s8, 0
	s_nop 0
	v_writelane_b32 v250, s5, 55
	s_cselect_b64 s[4:5], -1, 0
	v_writelane_b32 v250, s4, 56
	s_nop 1
	v_writelane_b32 v250, s5, 57
	s_lshl_b32 s4, s8, 8
	s_add_u32 s2, s2, s4
	s_addc_u32 s3, s3, 0
	s_add_u32 s4, s2, 0x1400
	s_addc_u32 s5, s3, 0
	v_writelane_b32 v250, s4, 58
	s_add_u32 s2, s2, 0x2400
	s_addc_u32 s3, s3, 0
	v_writelane_b32 v250, s5, 59
	v_writelane_b32 v250, s2, 60
	s_nop 1
	v_writelane_b32 v250, s3, 61
	s_add_u32 s2, s18, 0xf598400
	s_addc_u32 s3, s19, 0
	v_writelane_b32 v250, s2, 62
	s_nop 1
	v_writelane_b32 v250, s3, 63
	s_add_u32 s2, s18, 0xf598500
	s_addc_u32 s3, s19, 0
	v_writelane_b32 v251, s2, 0
	s_cmpk_lt_i32 s52, 0x840
	s_nop 0
	v_writelane_b32 v251, s3, 1
	s_cselect_b64 s[2:3], -1, 0
	v_writelane_b32 v251, s2, 2
	s_cmpk_lt_i32 s52, 0xa1
	s_nop 0
	v_writelane_b32 v251, s3, 3
	s_cselect_b64 s[2:3], -1, 0
	s_ashr_i32 s53, s52, 31
	v_writelane_b32 v251, s2, 4
	s_cmpk_lt_i32 s52, 0x5ac
	s_nop 0
	v_writelane_b32 v251, s3, 5
	s_cselect_b64 s[2:3], -1, 0
	v_writelane_b32 v251, s2, 6
	s_nop 1
	v_writelane_b32 v251, s3, 7
	s_lshr_b32 s2, s53, 29
	s_add_i32 s2, s52, s2
	s_ashr_i32 s3, s2, 3
	s_and_b32 s2, s2, -8
	s_sub_i32 s2, s52, s2
	s_mul_i32 s4, s2, 0xb5
	s_add_i32 s4, s4, 4
	s_cmpk_lt_i32 s52, 0x100
	s_cselect_b64 s[6:7], -1, 0
	v_writelane_b32 v251, s6, 8
	s_lshl_b32 s5, s2, 5
	s_nop 0
	v_writelane_b32 v251, s7, 9
	s_lshl_b32 s6, s52, 9
	v_writelane_b32 v251, s6, 10
	s_cmpk_lt_i32 s52, 0x294
	s_mul_i32 s6, s2, 0xffffff9d
	s_cselect_b64 s[8:9], -1, 0
	s_add_i32 s6, s4, s6
	s_cmp_lt_i32 s2, 4
	s_mul_i32 s7, s2, 0xb6
	s_cselect_b32 s4, s7, s4
	s_mul_i32 s7, s2, 0x53
	s_cselect_b32 s6, s7, s6
	s_add_i32 s4, s4, s3
	v_writelane_b32 v251, s8, 11
	s_mul_hi_i32 s7, s4, 0x2e8ba2e9
	s_nop 0
	v_writelane_b32 v251, s9, 12
	s_lshr_b32 s8, s7, 31
	s_ashr_i32 s7, s7, 4
	s_add_i32 s7, s7, s8
	s_mul_i32 s8, s7, 0x58
	s_lshl_b32 s7, s7, 2
	s_sub_i32 s4, s4, s8
	s_sub_i32 s8, 0x42, s7
	s_min_u32 s8, s8, 4
	s_cmp_lt_i32 s2, 0
	s_mul_i32 s2, s2, 33
	s_cselect_b32 s2, s2, s5
	s_add_i32 s2, s2, s3
	s_ashr_i32 s5, s2, 31
	s_lshr_b32 s5, s5, 28
	s_add_i32 s5, s2, s5
	s_and_b32 s9, s5, 0xfff0
	s_sub_i32 s2, s2, s9
	s_bfe_i32 s9, s2, 0x80000
	s_bfe_u32 s9, s9, 0x2000d
	s_add_i32 s9, s2, s9
	s_add_i32 s6, s6, s3
	s_and_b32 s10, s9, 0xfc
	s_mul_hi_i32 s3, s6, 0x66666667
	s_sub_i32 s2, s2, s10
	s_lshr_b32 s10, s3, 31
	s_ashr_i32 s3, s3, 4
	s_add_i32 s3, s3, s10
	s_mul_i32 s10, s3, 40
	s_ashr_i32 s5, s5, 4
	s_sub_i32 s6, s6, s10
	s_lshl_b32 s5, s5, 2
	s_bfe_i32 s9, s9, 0x80000
	s_sext_i32_i8 s2, s2
	s_lshl_b32 s10, s3, 2
	s_sext_i32_i16 s9, s9
	s_add_i32 s14, s5, s2
	s_sub_i32 s2, 0x42, s10
	s_min_u32 s11, s2, 4
	s_ashr_i32 s2, s9, 2
	v_writelane_b32 v251, s2, 13
	s_lshr_b32 s2, s9, 2
	s_bfe_i64 s[2:3], s[2:3], 0x100000
	v_cvt_f32_ubyte0_e32 v2, s8
	v_cvt_f32_i32_e32 v1, s4
	v_rcp_iflag_f32_e32 v3, v2
	s_lshl_b64 s[2:3], s[2:3], 19
	v_writelane_b32 v251, s2, 14
	s_ashr_i32 s15, s14, 31
	v_mul_f32_e32 v3, v1, v3
	v_writelane_b32 v251, s3, 15
	s_ashr_i32 s2, s4, 30
	s_or_b32 s5, s2, 1
	s_mov_b32 s2, s14
	v_writelane_b32 v251, s2, 16
	v_trunc_f32_e32 v3, v3
	v_fma_f32 v1, -v3, v2, v1
	v_writelane_b32 v251, s3, 17
	s_lshl_b64 s[2:3], s[14:15], 19
	v_writelane_b32 v251, s2, 18
	s_nop 1
	v_writelane_b32 v251, s3, 19
	v_cmp_ge_f32_e64 s[2:3], |v1|, v2
	v_cvt_i32_f32_e32 v1, v3
	s_and_b64 s[2:3], s[2:3], exec
	s_cselect_b32 s2, s5, 0
	v_cvt_f32_ubyte0_e32 v2, s11
	v_readfirstlane_b32 s3, v1
	s_add_i32 s2, s3, s2
	s_mul_i32 s3, s2, s8
	s_sub_i32 s3, s4, s3
	s_sext_i32_i8 s3, s3
	v_cvt_f32_i32_e32 v1, s6
	v_rcp_iflag_f32_e32 v3, v2
	s_bfe_i64 s[4:5], s[2:3], 0x80000
	s_lshl_b64 s[4:5], s[4:5], 19
	s_add_i32 s8, s7, s3
	v_writelane_b32 v251, s4, 20
	s_ashr_i32 s9, s8, 31
	v_mul_f32_e32 v3, v1, v3
	v_writelane_b32 v251, s5, 21
	s_mov_b32 s4, s8
	v_writelane_b32 v251, s4, 22
	v_trunc_f32_e32 v3, v3
	v_fma_f32 v1, -v3, v2, v1
	v_writelane_b32 v251, s5, 23
	s_lshl_b64 s[4:5], s[8:9], 19
	v_writelane_b32 v251, s4, 24
	s_ashr_i32 s3, s6, 30
	s_or_b32 s3, s3, 1
	v_writelane_b32 v251, s5, 25
	v_cmp_ge_f32_e64 s[4:5], |v1|, v2
	v_cvt_i32_f32_e32 v1, v3
	s_and_b64 s[4:5], s[4:5], exec
	s_sext_i32_i8 s2, s2
	v_writelane_b32 v251, s2, 26
	s_cselect_b32 s2, s3, 0
	v_readfirstlane_b32 s3, v1
	s_add_i32 s2, s3, s2
	s_mul_i32 s3, s2, s11
	s_sub_i32 s3, s6, s3
	s_sext_i32_i8 s3, s3
	s_add_i32 s3, s10, s3
	v_writelane_b32 v251, s3, 27
	s_sext_i32_i8 s2, s2
	v_writelane_b32 v251, s2, 28
	s_lshl_b32 s2, s52, 3
	v_writelane_b32 v251, s2, 29
	s_add_u32 s2, s18, 0x2f00000
	v_writelane_b32 v251, s2, 30
	s_addc_u32 s2, s19, 0
	v_writelane_b32 v251, s2, 31
	s_lshl_b32 s2, s52, 1
	v_writelane_b32 v251, s2, 32
	s_add_u32 s2, s18, 0xf599000
	v_writelane_b32 v251, s2, 33
	s_addc_u32 s2, s19, 0
	v_writelane_b32 v251, s2, 34
	s_add_u32 s2, s16, 0x4b6c000
	v_writelane_b32 v251, s2, 35
	s_addc_u32 s2, s17, 0
	v_writelane_b32 v251, s2, 36
	s_add_u32 s2, s16, 0x4b00000
	v_writelane_b32 v251, s2, 37
	s_addc_u32 s2, s17, 0
	v_writelane_b32 v251, s2, 38
	s_add_u32 s2, s16, 0x4b0c000
	v_writelane_b32 v251, s2, 39
	s_addc_u32 s2, s17, 0
	v_writelane_b32 v251, s2, 40
	s_add_i32 s2, 0, 0x20000
	s_load_dwordx8 s[4:11], s[0:1], 0xc0
	v_writelane_b32 v251, s2, 41
	s_add_i32 s2, 0, 0x20004
	v_writelane_b32 v251, s2, 42
	s_add_i32 s2, 0, 0x20040
	v_writelane_b32 v251, s2, 43
	s_add_i32 s2, 0, 0x19800
	v_writelane_b32 v251, s2, 44
	s_waitcnt lgkmcnt(0)
	v_writelane_b32 v251, s4, 45
	s_add_i32 s56, 0, 0x11800
	s_mov_b64 s[18:19], s[20:21]
	v_writelane_b32 v251, s5, 46
	v_writelane_b32 v251, s6, 47
	v_writelane_b32 v251, s7, 48
	v_writelane_b32 v251, s8, 49
	v_writelane_b32 v251, s9, 50
	v_writelane_b32 v251, s10, 51
	v_writelane_b32 v251, s11, 52
	v_writelane_b32 v251, s60, 53
	v_mbcnt_lo_u32_b32 v1, -1, 0
	v_mbcnt_hi_u32_b32 v244, -1, v1
	v_writelane_b32 v251, s61, 54
	v_writelane_b32 v251, s62, 55
	v_writelane_b32 v251, s63, 56
	v_writelane_b32 v251, s64, 57
	v_writelane_b32 v251, s65, 58
	v_writelane_b32 v251, s66, 59
	v_writelane_b32 v252, s71, 0
	v_writelane_b32 v251, s67, 60
	v_writelane_b32 v252, s72, 1
	v_writelane_b32 v251, s68, 61
	v_writelane_b32 v252, s73, 2
	v_writelane_b32 v251, s69, 62
	v_writelane_b32 v252, s74, 3
	v_writelane_b32 v251, s70, 63
	v_writelane_b32 v252, s75, 4
	s_load_dwordx16 s[80:95], s[0:1], 0x40
	s_load_dwordx16 s[60:75], s[0:1], 0x80
	v_mov_b32_e32 v1, 0x9000
	s_waitcnt lgkmcnt(0)
	v_writelane_b32 v252, s60, 5
	s_nop 1
	v_writelane_b32 v252, s61, 6
	v_writelane_b32 v252, s62, 7
	v_writelane_b32 v252, s63, 8
	v_writelane_b32 v252, s64, 9
	v_writelane_b32 v252, s65, 10
	v_writelane_b32 v252, s66, 11
	v_writelane_b32 v252, s67, 12
	v_writelane_b32 v252, s68, 13
	v_writelane_b32 v252, s69, 14
	v_writelane_b32 v252, s70, 15
	v_writelane_b32 v252, s71, 16
	v_writelane_b32 v252, s72, 17
	v_writelane_b32 v252, s73, 18
	v_writelane_b32 v252, s74, 19
	v_writelane_b32 v252, s75, 20
	v_writelane_b32 v252, s30, 21
	s_mov_b64 s[68:69], s[22:23]
	s_mov_b64 s[70:71], s[38:39]
	v_writelane_b32 v252, s31, 22
	v_writelane_b32 v252, s24, 23
	s_nop 1
	v_writelane_b32 v252, s25, 24
	v_writelane_b32 v252, s26, 25
	s_nop 1
	v_writelane_b32 v252, s27, 26
	v_writelane_b32 v252, s28, 27
	s_nop 1
	v_writelane_b32 v252, s29, 28
	v_writelane_b32 v252, s12, 29
	s_nop 1
	v_writelane_b32 v252, s13, 30
	v_writelane_b32 v252, s56, 31
	v_writelane_b32 v252, s52, 32
	s_nop 1
	v_writelane_b32 v252, s53, 33
	v_writelane_b32 v252, s18, 34
	s_nop 1
	v_writelane_b32 v252, s19, 35
	v_writelane_b32 v252, s50, 36
	s_nop 1
	v_writelane_b32 v252, s51, 37
	v_writelane_b32 v252, s68, 38
	s_nop 1
	v_writelane_b32 v252, s69, 39
	v_writelane_b32 v252, s70, 40
	s_nop 1
	v_writelane_b32 v252, s71, 41
	s_branch .LBB0_8
.LBB0_7:
	v_readlane_b32 s18, v255, 63
	s_cmp_eq_u32 s76, 3
	s_cselect_b32 s19, 1, 0
	s_min_u32 s19, s19, s18
	s_sub_i32 s18, s18, s19
	s_sub_i32 s76, s76, s19
	v_writelane_b32 v255, s18, 63
	v_readlane_b32 s18, v252, 34
	s_add_i32 s76, s76, 1
	v_readlane_b32 s19, v252, 35
	v_readlane_b32 s12, v252, 29
	s_cmp_ge_i32 s76, s19
	v_readlane_b32 s13, v252, 30
	s_mov_b64 s[68:69], s[42:43]
	s_mov_b64 s[70:71], s[44:45]
	s_cbranch_scc0 .LBB0_8
	s_getpc_b64 s[98:99]

.LBB0_91:
	s_lshl_b32 s0, s0, 5
	s_and_b32 s10, s0, 0x60
	s_lshl_b32 s7, s6, 13
	s_lshl_b32 s11, s10, 7
	s_add_u32 s0, s72, 0x5195000
	s_addc_u32 s1, s73, 0
	s_add_i32 m0, s26, 0x18000
	v_lshl_add_u64 v[8:9], v[8:9], 0, s[78:79]
	s_waitcnt vmcnt(4)
	s_barrier
	global_load_lds_dwordx4 v[8:9], off
	v_lshl_add_u64 v[6:7], v[6:7], 0, s[78:79]
	s_add_i32 m0, s26, 0x1a000
	s_add_i32 s30, s26, 0x8000
	s_add_i32 s31, s26, 0xa000
	global_load_lds_dwordx4 v[6:7], off
	v_lshl_add_u64 v[4:5], v[4:5], 0, s[78:79]
	s_mov_b32 m0, s30
	s_add_u32 s8, s16, 0x40080
	global_load_lds_dwordx4 v[4:5], off
	v_lshl_add_u64 v[2:3], v[2:3], 0, s[78:79]
	s_mov_b32 m0, s31
	s_addc_u32 s9, s17, 0
	global_load_lds_dwordx4 v[2:3], off
	s_add_i32 m0, s26, 0x1c000
	v_lshl_add_u64 v[2:3], s[8:9], 0, v[132:133]
	global_load_lds_dwordx4 v[2:3], off
	v_lshl_add_u64 v[2:3], s[8:9], 0, v[130:131]
	s_add_i32 m0, s26, 0x1e000
	v_mov_b32_e32 v135, v191
	global_load_lds_dwordx4 v[2:3], off
	v_lshrrev_b32_e32 v2, 1, v10
	v_and_b32_e32 v2, 24, v2
	v_and_b32_e32 v3, 15, v10
	v_lshlrev_b32_e32 v4, 1, v2
	v_lshl_or_b32 v138, s6, 6, v3
	v_lshl_or_b32 v3, v3, 6, v4
	v_lshlrev_b32_e32 v4, 2, v10
	v_and_b32_e32 v4, 32, v4
	v_bitop3_b32 v5, v3, s7, v4 bitop3:0xde
	v_bitop3_b32 v139, v3, s11, v4 bitop3:0xde
	v_lshlrev_b32_e32 v3, 14, v14
	v_and_b32_e32 v3, 0xffff8000, v3
	v_lshl_add_u32 v3, v15, 11, v3
	v_and_b32_e32 v4, 1, v14
	v_lshl_or_b32 v3, v4, 6, v3
	v_lshl_add_u32 v134, v16, 1, v3
	v_lshlrev_b32_e32 v3, 14, v11
	v_and_b32_e32 v3, 0xffff8000, v3
	s_waitcnt vmcnt(6)
	v_lshl_add_u32 v3, v12, 11, v3
	v_and_b32_e32 v4, 1, v11
	v_lshl_or_b32 v3, v4, 6, v3
	v_readlane_b32 s6, v251, 22
	v_lshl_add_u32 v136, v13, 1, v3
	v_mov_b32_e32 v137, v191
	s_mov_b32 s37, 0
	v_add_u32_e32 v140, 0, v5
	s_lshl_b32 s96, s10, 1
	v_lshlrev_b32_e32 v190, 1, v2
	v_readlane_b32 s35, v251, 26
	s_mov_b32 s36, s6
	s_barrier
	v_readlane_b32 s7, v251, 23

.LBB0_99:
	s_add_u32 s16, s14, 0xfffc0080
	s_addc_u32 s17, s15, -1
	s_add_i32 s45, 0, 0x10000
	v_add_u32_e32 v141, s45, v139
	ds_read_b128 v[142:145], v141
	ds_read_b128 v[146:149], v141 offset:1024
	ds_read_b128 v[150:153], v141 offset:2048
	ds_read_b128 v[154:157], v141 offset:3072
	s_cmp_eq_u32 s44, 12
	s_cselect_b32 s19, s9, s17
	s_cselect_b32 s18, s40, s16
	s_cselect_b32 s17, s7, s43
	s_cselect_b32 s16, s41, s42
	v_lshl_add_u64 v[192:193], s[14:15], 0, v[134:135]
	s_add_i32 m0, s26, 0xc000
	ds_read_b128 v[158:161], v140
	ds_read_b128 v[162:165], v140 offset:1024
	ds_read_b128 v[166:169], v140 offset:2048
	ds_read_b128 v[170:173], v140 offset:3072
	ds_read_b128 v[174:177], v140 offset:4096
	ds_read_b128 v[178:181], v140 offset:5120
	ds_read_b128 v[182:185], v140 offset:6144
	ds_read_b128 v[186:189], v140 offset:7168
	global_load_lds_dwordx4 v[192:193], off
	v_lshl_add_u64 v[192:193], s[14:15], 0, v[136:137]
	s_add_i32 m0, s26, 0xe000
	s_nop 0
	global_load_lds_dwordx4 v[192:193], off
	s_waitcnt lgkmcnt(8)
	s_barrier
	s_waitcnt lgkmcnt(0)
	s_setprio 1
	s_waitcnt lgkmcnt(0)
	v_mfma_f32_16x16x32_bf16 v[126:129], v[142:145], v[158:161], v[126:129]
	v_mfma_f32_16x16x32_bf16 v[122:125], v[150:153], v[158:161], v[122:125]
	v_mfma_f32_16x16x32_bf16 v[110:113], v[142:145], v[166:169], v[110:113]
	v_mfma_f32_16x16x32_bf16 v[106:109], v[150:153], v[166:169], v[106:109]
	v_mfma_f32_16x16x32_bf16 v[94:97], v[142:145], v[174:177], v[94:97]
	v_mfma_f32_16x16x32_bf16 v[90:93], v[150:153], v[174:177], v[90:93]
	v_mfma_f32_16x16x32_bf16 v[78:81], v[142:145], v[182:185], v[78:81]
	v_mfma_f32_16x16x32_bf16 v[74:77], v[150:153], v[182:185], v[74:77]
	v_mfma_f32_16x16x32_bf16 v[126:129], v[146:149], v[162:165], v[126:129]
	v_mfma_f32_16x16x32_bf16 v[122:125], v[154:157], v[162:165], v[122:125]
	v_mfma_f32_16x16x32_bf16 v[110:113], v[146:149], v[170:173], v[110:113]
	v_mfma_f32_16x16x32_bf16 v[106:109], v[154:157], v[170:173], v[106:109]
	v_mfma_f32_16x16x32_bf16 v[94:97], v[146:149], v[178:181], v[94:97]
	v_mfma_f32_16x16x32_bf16 v[90:93], v[154:157], v[178:181], v[90:93]
	v_mfma_f32_16x16x32_bf16 v[78:81], v[146:149], v[186:189], v[78:81]
	v_mfma_f32_16x16x32_bf16 v[74:77], v[154:157], v[186:189], v[74:77]
	s_setprio 0
	s_barrier
	s_add_i32 s48, 0, 0x14000
	s_add_i32 s45, s45, s25
	v_add_u32_e32 v141, s48, v139
	v_lshl_add_u64 v[192:193], s[16:17], 0, v[132:133]
	s_mov_b32 m0, s45
	ds_read_b128 v[204:207], v141
	ds_read_b128 v[208:211], v141 offset:1024
	ds_read_b128 v[212:215], v141 offset:2048
	ds_read_b128 v[216:219], v141 offset:3072
	global_load_lds_dwordx4 v[192:193], off
	v_lshl_add_u64 v[194:195], s[16:17], 0, v[130:131]
	s_add_i32 m0, s45, 0x2000
	s_nop 0
	global_load_lds_dwordx4 v[194:195], off
	s_barrier
	s_waitcnt lgkmcnt(0)
	s_setprio 1
	s_waitcnt lgkmcnt(0)
	v_mfma_f32_16x16x32_bf16 v[118:121], v[204:207], v[158:161], v[118:121]
	v_mfma_f32_16x16x32_bf16 v[114:117], v[212:215], v[158:161], v[114:117]
	v_mfma_f32_16x16x32_bf16 v[102:105], v[204:207], v[166:169], v[102:105]
	v_mfma_f32_16x16x32_bf16 v[98:101], v[212:215], v[166:169], v[98:101]
	v_mfma_f32_16x16x32_bf16 v[86:89], v[204:207], v[174:177], v[86:89]
	v_mfma_f32_16x16x32_bf16 v[82:85], v[212:215], v[174:177], v[82:85]
	v_mfma_f32_16x16x32_bf16 v[70:73], v[204:207], v[182:185], v[70:73]
	v_mfma_f32_16x16x32_bf16 v[66:69], v[212:215], v[182:185], v[66:69]
	v_mfma_f32_16x16x32_bf16 v[118:121], v[208:211], v[162:165], v[118:121]
	v_mfma_f32_16x16x32_bf16 v[114:117], v[216:219], v[162:165], v[114:117]
	v_mfma_f32_16x16x32_bf16 v[102:105], v[208:211], v[170:173], v[102:105]
	v_mfma_f32_16x16x32_bf16 v[98:101], v[216:219], v[170:173], v[98:101]
	v_mfma_f32_16x16x32_bf16 v[86:89], v[208:211], v[178:181], v[86:89]
	v_mfma_f32_16x16x32_bf16 v[82:85], v[216:219], v[178:181], v[82:85]
	v_mfma_f32_16x16x32_bf16 v[70:73], v[208:211], v[186:189], v[70:73]
	v_mfma_f32_16x16x32_bf16 v[66:69], v[216:219], v[186:189], v[66:69]
	s_setprio 0
	s_mov_b32 m0, s26
	v_lshl_add_u64 v[196:197], s[18:19], 0, v[132:133]
	s_barrier
	ds_read_b128 v[158:161], v140 offset:16384
	ds_read_b128 v[162:165], v140 offset:17408
	ds_read_b128 v[166:169], v140 offset:18432
	ds_read_b128 v[170:173], v140 offset:19456
	ds_read_b128 v[174:177], v140 offset:20480
	ds_read_b128 v[178:181], v140 offset:21504
	ds_read_b128 v[182:185], v140 offset:22528
	ds_read_b128 v[186:189], v140 offset:23552
	global_load_lds_dwordx4 v[196:197], off
	v_lshl_add_u64 v[200:201], s[18:19], 0, v[130:131]
	s_mov_b32 m0, s27
	s_nop 0
	global_load_lds_dwordx4 v[200:201], off
	s_barrier
	s_waitcnt lgkmcnt(0)
	s_setprio 1
	s_waitcnt lgkmcnt(0)
	v_mfma_f32_16x16x32_bf16 v[62:65], v[142:145], v[158:161], v[62:65]
	v_mfma_f32_16x16x32_bf16 v[58:61], v[150:153], v[158:161], v[58:61]
	v_mfma_f32_16x16x32_bf16 v[46:49], v[142:145], v[166:169], v[46:49]
	v_mfma_f32_16x16x32_bf16 v[42:45], v[150:153], v[166:169], v[42:45]
	v_mfma_f32_16x16x32_bf16 v[30:33], v[142:145], v[174:177], v[30:33]
	v_mfma_f32_16x16x32_bf16 v[26:29], v[150:153], v[174:177], v[26:29]
	v_mfma_f32_16x16x32_bf16 v[14:17], v[142:145], v[182:185], v[14:17]
	v_mfma_f32_16x16x32_bf16 v[10:13], v[150:153], v[182:185], v[10:13]
	v_mfma_f32_16x16x32_bf16 v[62:65], v[146:149], v[162:165], v[62:65]
	v_mfma_f32_16x16x32_bf16 v[58:61], v[154:157], v[162:165], v[58:61]
	v_mfma_f32_16x16x32_bf16 v[46:49], v[146:149], v[170:173], v[46:49]
	v_mfma_f32_16x16x32_bf16 v[42:45], v[154:157], v[170:173], v[42:45]
	v_mfma_f32_16x16x32_bf16 v[30:33], v[146:149], v[178:181], v[30:33]
	v_mfma_f32_16x16x32_bf16 v[26:29], v[154:157], v[178:181], v[26:29]
	v_mfma_f32_16x16x32_bf16 v[14:17], v[146:149], v[186:189], v[14:17]
	v_mfma_f32_16x16x32_bf16 v[10:13], v[154:157], v[186:189], v[10:13]
	s_setprio 0
	s_barrier
	s_add_u32 s46, s16, 0x40000
	s_addc_u32 s47, s17, 0
	s_add_i32 s45, s48, s25
	v_lshl_add_u64 v[142:143], s[46:47], 0, v[132:133]
	s_mov_b32 m0, s45
	s_nop 0
	global_load_lds_dwordx4 v[142:143], off
	v_lshl_add_u64 v[142:143], s[46:47], 0, v[130:131]
	s_add_i32 m0, s45, 0x2000
	s_nop 0
	global_load_lds_dwordx4 v[142:143], off
	s_waitcnt vmcnt(6)
	s_barrier
	s_setprio 1
	v_mfma_f32_16x16x32_bf16 v[54:57], v[204:207], v[158:161], v[54:57]
	v_mfma_f32_16x16x32_bf16 v[50:53], v[212:215], v[158:161], v[50:53]
	v_mfma_f32_16x16x32_bf16 v[38:41], v[204:207], v[166:169], v[38:41]
	v_mfma_f32_16x16x32_bf16 v[34:37], v[212:215], v[166:169], v[34:37]
	v_mfma_f32_16x16x32_bf16 v[22:25], v[204:207], v[174:177], v[22:25]
	v_mfma_f32_16x16x32_bf16 v[18:21], v[212:215], v[174:177], v[18:21]
	v_mfma_f32_16x16x32_bf16 v[6:9], v[204:207], v[182:185], v[6:9]
	v_mfma_f32_16x16x32_bf16 v[2:5], v[212:215], v[182:185], v[2:5]
	v_mfma_f32_16x16x32_bf16 v[54:57], v[208:211], v[162:165], v[54:57]
	v_mfma_f32_16x16x32_bf16 v[50:53], v[216:219], v[162:165], v[50:53]
	v_mfma_f32_16x16x32_bf16 v[38:41], v[208:211], v[170:173], v[38:41]
	v_mfma_f32_16x16x32_bf16 v[34:37], v[216:219], v[170:173], v[34:37]
	v_mfma_f32_16x16x32_bf16 v[22:25], v[208:211], v[178:181], v[22:25]
	v_mfma_f32_16x16x32_bf16 v[18:21], v[216:219], v[178:181], v[18:21]
	v_mfma_f32_16x16x32_bf16 v[6:9], v[208:211], v[186:189], v[6:9]
	v_mfma_f32_16x16x32_bf16 v[2:5], v[216:219], v[186:189], v[2:5]
	s_setprio 0
	s_add_i32 s45, 0, 0x18000
	v_add_u32_e32 v141, s45, v139
	s_barrier
	ds_read_b128 v[142:145], v141
	ds_read_b128 v[146:149], v141 offset:1024
	ds_read_b128 v[150:153], v141 offset:2048
	ds_read_b128 v[154:157], v141 offset:3072
	s_add_u32 s18, s18, 0x40000
	s_addc_u32 s19, s19, 0
	s_mov_b32 m0, s28
	v_lshl_add_u64 v[204:205], s[18:19], 0, v[132:133]
	ds_read_b128 v[158:161], v140 offset:32768
	ds_read_b128 v[162:165], v140 offset:33792
	ds_read_b128 v[166:169], v140 offset:34816
	ds_read_b128 v[170:173], v140 offset:35840
	ds_read_b128 v[174:177], v140 offset:36864
	ds_read_b128 v[178:181], v140 offset:37888
	ds_read_b128 v[182:185], v140 offset:38912
	ds_read_b128 v[186:189], v140 offset:39936
	global_load_lds_dwordx4 v[204:205], off
	v_lshl_add_u64 v[204:205], s[18:19], 0, v[130:131]
	s_mov_b32 m0, s29
	s_nop 0
	global_load_lds_dwordx4 v[204:205], off
	s_waitcnt lgkmcnt(8)
	s_barrier
	s_waitcnt lgkmcnt(0)
	s_setprio 1
	s_waitcnt lgkmcnt(0)
	v_mfma_f32_16x16x32_bf16 v[126:129], v[142:145], v[158:161], v[126:129]
	v_mfma_f32_16x16x32_bf16 v[122:125], v[150:153], v[158:161], v[122:125]
	v_mfma_f32_16x16x32_bf16 v[110:113], v[142:145], v[166:169], v[110:113]
	v_mfma_f32_16x16x32_bf16 v[106:109], v[150:153], v[166:169], v[106:109]
	v_mfma_f32_16x16x32_bf16 v[94:97], v[142:145], v[174:177], v[94:97]
	v_mfma_f32_16x16x32_bf16 v[90:93], v[150:153], v[174:177], v[90:93]
	v_mfma_f32_16x16x32_bf16 v[78:81], v[142:145], v[182:185], v[78:81]
	v_mfma_f32_16x16x32_bf16 v[74:77], v[150:153], v[182:185], v[74:77]
	v_mfma_f32_16x16x32_bf16 v[126:129], v[146:149], v[162:165], v[126:129]
	v_mfma_f32_16x16x32_bf16 v[122:125], v[154:157], v[162:165], v[122:125]
	v_mfma_f32_16x16x32_bf16 v[110:113], v[146:149], v[170:173], v[110:113]
	v_mfma_f32_16x16x32_bf16 v[106:109], v[154:157], v[170:173], v[106:109]
	v_mfma_f32_16x16x32_bf16 v[94:97], v[146:149], v[178:181], v[94:97]
	v_mfma_f32_16x16x32_bf16 v[90:93], v[154:157], v[178:181], v[90:93]
	v_mfma_f32_16x16x32_bf16 v[78:81], v[146:149], v[186:189], v[78:81]
	v_mfma_f32_16x16x32_bf16 v[74:77], v[154:157], v[186:189], v[74:77]
	s_setprio 0
	s_barrier
	s_add_i32 s18, 0, 0x1c000
	s_add_i32 s19, s45, s25
	v_add_u32_e32 v141, s18, v139
	v_lshl_add_u64 v[192:193], v[192:193], 0, s[78:79]
	s_mov_b32 m0, s19
	ds_read_b128 v[204:207], v141
	ds_read_b128 v[208:211], v141 offset:1024
	ds_read_b128 v[212:215], v141 offset:2048
	ds_read_b128 v[216:219], v141 offset:3072
	global_load_lds_dwordx4 v[192:193], off
	v_lshl_add_u64 v[192:193], v[194:195], 0, s[78:79]
	s_add_i32 m0, s19, 0x2000
	s_nop 0
	global_load_lds_dwordx4 v[192:193], off
	s_barrier
	s_waitcnt lgkmcnt(0)
	s_setprio 1
	s_waitcnt lgkmcnt(0)
	v_mfma_f32_16x16x32_bf16 v[118:121], v[204:207], v[158:161], v[118:121]
	v_mfma_f32_16x16x32_bf16 v[114:117], v[212:215], v[158:161], v[114:117]
	v_mfma_f32_16x16x32_bf16 v[102:105], v[204:207], v[166:169], v[102:105]
	v_mfma_f32_16x16x32_bf16 v[98:101], v[212:215], v[166:169], v[98:101]
	v_mfma_f32_16x16x32_bf16 v[86:89], v[204:207], v[174:177], v[86:89]
	v_mfma_f32_16x16x32_bf16 v[82:85], v[212:215], v[174:177], v[82:85]
	v_mfma_f32_16x16x32_bf16 v[70:73], v[204:207], v[182:185], v[70:73]
	v_mfma_f32_16x16x32_bf16 v[66:69], v[212:215], v[182:185], v[66:69]
	v_mfma_f32_16x16x32_bf16 v[118:121], v[208:211], v[162:165], v[118:121]
	v_mfma_f32_16x16x32_bf16 v[114:117], v[216:219], v[162:165], v[114:117]
	v_mfma_f32_16x16x32_bf16 v[102:105], v[208:211], v[170:173], v[102:105]
	v_mfma_f32_16x16x32_bf16 v[98:101], v[216:219], v[170:173], v[98:101]
	v_mfma_f32_16x16x32_bf16 v[86:89], v[208:211], v[178:181], v[86:89]
	v_mfma_f32_16x16x32_bf16 v[82:85], v[216:219], v[178:181], v[82:85]
	v_mfma_f32_16x16x32_bf16 v[70:73], v[208:211], v[186:189], v[70:73]
	v_mfma_f32_16x16x32_bf16 v[66:69], v[216:219], v[186:189], v[66:69]
	s_setprio 0
	s_mov_b32 m0, s30
	v_lshl_add_u64 v[192:193], v[196:197], 0, s[78:79]
	s_barrier
	ds_read_b128 v[158:161], v140 offset:49152
	ds_read_b128 v[162:165], v140 offset:50176
	ds_read_b128 v[166:169], v140 offset:51200
	ds_read_b128 v[170:173], v140 offset:52224
	ds_read_b128 v[174:177], v140 offset:53248
	ds_read_b128 v[178:181], v140 offset:54272
	ds_read_b128 v[182:185], v140 offset:55296
	ds_read_b128 v[186:189], v140 offset:56320
	global_load_lds_dwordx4 v[192:193], off
	v_lshl_add_u64 v[192:193], v[200:201], 0, s[78:79]
	s_mov_b32 m0, s31
	s_nop 0
	global_load_lds_dwordx4 v[192:193], off
	s_barrier
	s_waitcnt lgkmcnt(0)
	s_setprio 1
	s_waitcnt lgkmcnt(0)
	v_mfma_f32_16x16x32_bf16 v[62:65], v[142:145], v[158:161], v[62:65]
	v_mfma_f32_16x16x32_bf16 v[58:61], v[150:153], v[158:161], v[58:61]
	v_mfma_f32_16x16x32_bf16 v[46:49], v[142:145], v[166:169], v[46:49]
	v_mfma_f32_16x16x32_bf16 v[42:45], v[150:153], v[166:169], v[42:45]
	v_mfma_f32_16x16x32_bf16 v[30:33], v[142:145], v[174:177], v[30:33]
	v_mfma_f32_16x16x32_bf16 v[26:29], v[150:153], v[174:177], v[26:29]
	v_mfma_f32_16x16x32_bf16 v[14:17], v[142:145], v[182:185], v[14:17]
	v_mfma_f32_16x16x32_bf16 v[10:13], v[150:153], v[182:185], v[10:13]
	v_mfma_f32_16x16x32_bf16 v[62:65], v[146:149], v[162:165], v[62:65]
	v_mfma_f32_16x16x32_bf16 v[58:61], v[154:157], v[162:165], v[58:61]
	v_mfma_f32_16x16x32_bf16 v[46:49], v[146:149], v[170:173], v[46:49]
	v_mfma_f32_16x16x32_bf16 v[42:45], v[154:157], v[170:173], v[42:45]
	v_mfma_f32_16x16x32_bf16 v[30:33], v[146:149], v[178:181], v[30:33]
	v_mfma_f32_16x16x32_bf16 v[26:29], v[154:157], v[178:181], v[26:29]
	v_mfma_f32_16x16x32_bf16 v[14:17], v[146:149], v[186:189], v[14:17]
	v_mfma_f32_16x16x32_bf16 v[10:13], v[154:157], v[186:189], v[10:13]
	s_setprio 0
	s_barrier
	s_add_u32 s16, s16, 0x40080
	s_addc_u32 s17, s17, 0
	s_add_i32 s18, s18, s25
	v_lshl_add_u64 v[142:143], s[16:17], 0, v[132:133]
	s_mov_b32 m0, s18
	s_nop 0
	global_load_lds_dwordx4 v[142:143], off
	v_lshl_add_u64 v[142:143], s[16:17], 0, v[130:131]
	s_add_i32 m0, s18, 0x2000
	s_nop 0
	global_load_lds_dwordx4 v[142:143], off
	s_waitcnt vmcnt(6)
	s_barrier
	s_setprio 1
	v_mfma_f32_16x16x32_bf16 v[54:57], v[204:207], v[158:161], v[54:57]
	v_mfma_f32_16x16x32_bf16 v[50:53], v[212:215], v[158:161], v[50:53]
	v_mfma_f32_16x16x32_bf16 v[38:41], v[204:207], v[166:169], v[38:41]
	v_mfma_f32_16x16x32_bf16 v[34:37], v[212:215], v[166:169], v[34:37]
	v_mfma_f32_16x16x32_bf16 v[22:25], v[204:207], v[174:177], v[22:25]
	v_mfma_f32_16x16x32_bf16 v[18:21], v[212:215], v[174:177], v[18:21]
	v_mfma_f32_16x16x32_bf16 v[6:9], v[204:207], v[182:185], v[6:9]
	v_mfma_f32_16x16x32_bf16 v[2:5], v[212:215], v[182:185], v[2:5]
	v_mfma_f32_16x16x32_bf16 v[54:57], v[208:211], v[162:165], v[54:57]
	v_mfma_f32_16x16x32_bf16 v[50:53], v[216:219], v[162:165], v[50:53]
	v_mfma_f32_16x16x32_bf16 v[38:41], v[208:211], v[170:173], v[38:41]
	v_mfma_f32_16x16x32_bf16 v[34:37], v[216:219], v[170:173], v[34:37]
	v_mfma_f32_16x16x32_bf16 v[22:25], v[208:211], v[178:181], v[22:25]
	v_mfma_f32_16x16x32_bf16 v[18:21], v[216:219], v[178:181], v[18:21]
	v_mfma_f32_16x16x32_bf16 v[6:9], v[208:211], v[186:189], v[6:9]
	v_mfma_f32_16x16x32_bf16 v[2:5], v[216:219], v[186:189], v[2:5]
	s_setprio 0
	s_add_i32 s44, s44, 2
	s_add_u32 s14, s14, 0x100
	s_addc_u32 s15, s15, 0
	s_add_u32 s42, s42, 0x100
	s_addc_u32 s43, s43, 0
	s_cmp_gt_u32 s44, 13
	s_barrier
	s_cbranch_scc0 .LBB0_99
	v_lshl_add_u32 v141, s37, 8, v138
	v_lshl_add_u32 v141, v141, 2, 0
	v_add_u32_e32 v142, 0x20040, v141
	ds_read2_b32 v[144:145], v142 offset1:16
	v_pk_mul_f32 v[124:125], v[128:129], v[124:125]
	v_pk_mul_f32 v[122:123], v[126:127], v[122:123]
	v_pk_mul_f32 v[114:115], v[118:119], v[114:115]
	v_pk_mul_f32 v[116:117], v[120:121], v[116:117]
	s_waitcnt lgkmcnt(0)
	v_mul_f32_e32 v146, 0xbfb8aa3b, v144
	v_pk_mul_f32 v[148:149], v[126:127], v[146:147] op_sel_hi:[1,0]
	v_pk_mul_f32 v[126:127], v[128:129], v[146:147] op_sel_hi:[1,0]
	v_pk_mul_f32 v[128:129], v[118:119], v[146:147] op_sel_hi:[1,0]
	v_pk_mul_f32 v[118:119], v[120:121], v[146:147] op_sel_hi:[1,0]
	v_exp_f32_e32 v128, v128
	v_exp_f32_e32 v129, v129
	v_exp_f32_e32 v148, v148
	v_exp_f32_e32 v149, v149
	v_exp_f32_e32 v126, v126
	v_exp_f32_e32 v127, v127
	v_exp_f32_e32 v118, v118
	v_exp_f32_e32 v119, v119
	v_pk_add_f32 v[128:129], v[128:129], 1.0 op_sel_hi:[1,0]
	v_pk_add_f32 v[120:121], v[148:149], 1.0 op_sel_hi:[1,0]
	v_pk_add_f32 v[126:127], v[126:127], 1.0 op_sel_hi:[1,0]
	v_rcp_f32_e32 v128, v128
	v_rcp_f32_e32 v129, v129
	v_pk_add_f32 v[118:119], v[118:119], 1.0 op_sel_hi:[1,0]
	v_rcp_f32_e32 v120, v120
	v_rcp_f32_e32 v121, v121
	v_rcp_f32_e32 v126, v126
	v_rcp_f32_e32 v127, v127
	v_rcp_f32_e32 v118, v118
	v_rcp_f32_e32 v119, v119
	v_mul_f32_e32 v144, v144, v144
	v_pk_mul_f32 v[114:115], v[114:115], v[144:145] op_sel_hi:[1,0]
	s_lshl_b32 s14, s35, 7
	v_pk_mul_f32 v[122:123], v[122:123], v[144:145] op_sel_hi:[1,0]
	v_pk_mul_f32 v[124:125], v[124:125], v[144:145] op_sel_hi:[1,0]
	v_pk_mul_f32 v[116:117], v[116:117], v[144:145] op_sel_hi:[1,0]
	v_pk_mul_f32 v[114:115], v[114:115], v[128:129]
	v_lshl_add_u32 v141, s36, 8, v138
	s_ashr_i32 s15, s14, 31
	v_pk_mul_f32 v[120:121], v[122:123], v[120:121]
	v_pk_mul_f32 v[122:123], v[124:125], v[126:127]
	v_pk_mul_f32 v[124:125], v[116:117], v[118:119]
	v_cvt_pk_bf16_f32 v118, v114, v115
	v_mov_b64_e32 v[114:115], s[0:1]
	s_movk_i32 s7, 0x1600
	v_cvt_pk_bf16_f32 v116, v120, v121
	v_mad_i64_i32 v[120:121], s[16:17], v141, s7, v[114:115]
	s_lshl_b64 s[14:15], s[14:15], 1
	v_lshl_add_u64 v[120:121], v[120:121], 0, s[14:15]
	v_lshl_add_u64 v[120:121], v[120:121], 0, s[96:97]
	v_lshl_add_u64 v[120:121], v[120:121], 0, v[190:191]
	v_cvt_pk_bf16_f32 v117, v122, v123
	v_cvt_pk_bf16_f32 v119, v124, v125
	global_store_dwordx4 v[120:121], v[116:119], off
	v_pk_mul_f32 v[108:109], v[112:113], v[108:109]
	v_pk_mul_f32 v[106:107], v[110:111], v[106:107]
	v_mul_f32_e32 v116, 0xbfb8aa3b, v145
	v_pk_mul_f32 v[120:121], v[110:111], v[116:117] op_sel_hi:[1,0]
	v_pk_mul_f32 v[110:111], v[112:113], v[116:117] op_sel_hi:[1,0]
	v_exp_f32_e32 v120, v120
	v_exp_f32_e32 v121, v121
	v_pk_mul_f32 v[112:113], v[102:103], v[116:117] op_sel_hi:[1,0]
	v_pk_mul_f32 v[98:99], v[102:103], v[98:99]
	v_pk_mul_f32 v[102:103], v[104:105], v[116:117] op_sel_hi:[1,0]
	v_exp_f32_e32 v110, v110
	v_exp_f32_e32 v111, v111
	v_exp_f32_e32 v112, v112
	v_exp_f32_e32 v113, v113
	v_exp_f32_e32 v102, v102
	v_exp_f32_e32 v103, v103
	v_pk_mul_f32 v[100:101], v[104:105], v[100:101]
	v_pk_add_f32 v[104:105], v[120:121], 1.0 op_sel_hi:[1,0]
	v_pk_add_f32 v[110:111], v[110:111], 1.0 op_sel_hi:[1,0]
	v_rcp_f32_e32 v104, v104
	v_rcp_f32_e32 v105, v105
	v_pk_add_f32 v[112:113], v[112:113], 1.0 op_sel_hi:[1,0]
	v_pk_add_f32 v[102:103], v[102:103], 1.0 op_sel_hi:[1,0]
	v_rcp_f32_e32 v110, v110
	v_rcp_f32_e32 v111, v111
	v_rcp_f32_e32 v112, v112
	v_rcp_f32_e32 v113, v113
	v_rcp_f32_e32 v102, v102
	v_rcp_f32_e32 v103, v103
	v_mul_f32_e32 v118, v145, v145
	v_pk_mul_f32 v[106:107], v[106:107], v[118:119] op_sel_hi:[1,0]
	v_pk_mul_f32 v[108:109], v[108:109], v[118:119] op_sel_hi:[1,0]
	v_pk_mul_f32 v[98:99], v[98:99], v[118:119] op_sel_hi:[1,0]
	v_pk_mul_f32 v[100:101], v[100:101], v[118:119] op_sel_hi:[1,0]
	v_pk_mul_f32 v[104:105], v[106:107], v[104:105]
	v_pk_mul_f32 v[106:107], v[108:109], v[110:111]
	v_pk_mul_f32 v[108:109], v[98:99], v[112:113]
	v_pk_mul_f32 v[102:103], v[100:101], v[102:103]
	v_or_b32_e32 v110, 16, v141
	v_cvt_pk_bf16_f32 v98, v104, v105
	ds_read2_b32 v[104:105], v142 offset0:32 offset1:48
	v_cvt_pk_bf16_f32 v101, v102, v103
	v_mad_i64_i32 v[102:103], s[16:17], v110, s7, v[114:115]
	v_lshl_add_u64 v[102:103], v[102:103], 0, s[14:15]
	v_lshl_add_u64 v[102:103], v[102:103], 0, s[96:97]
	v_lshl_add_u64 v[102:103], v[102:103], 0, v[190:191]
	v_cvt_pk_bf16_f32 v99, v106, v107
	v_cvt_pk_bf16_f32 v100, v108, v109
	global_store_dwordx4 v[102:103], v[98:101], off
	v_pk_mul_f32 v[92:93], v[96:97], v[92:93]
	v_pk_mul_f32 v[90:91], v[94:95], v[90:91]
	s_waitcnt lgkmcnt(0)
	v_mul_f32_e32 v98, 0xbfb8aa3b, v104
	v_pk_mul_f32 v[102:103], v[94:95], v[98:99] op_sel_hi:[1,0]
	v_pk_mul_f32 v[94:95], v[96:97], v[98:99] op_sel_hi:[1,0]
	v_pk_mul_f32 v[96:97], v[86:87], v[98:99] op_sel_hi:[1,0]
	v_pk_mul_f32 v[82:83], v[86:87], v[82:83]
	v_pk_mul_f32 v[86:87], v[88:89], v[98:99] op_sel_hi:[1,0]
	v_exp_f32_e32 v102, v102
	v_exp_f32_e32 v103, v103
	v_exp_f32_e32 v94, v94
	v_exp_f32_e32 v95, v95
	v_exp_f32_e32 v86, v86
	v_exp_f32_e32 v87, v87
	v_exp_f32_e32 v96, v96
	v_exp_f32_e32 v97, v97
	v_pk_mul_f32 v[84:85], v[88:89], v[84:85]
	v_pk_add_f32 v[88:89], v[102:103], 1.0 op_sel_hi:[1,0]
	v_pk_add_f32 v[94:95], v[94:95], 1.0 op_sel_hi:[1,0]
	v_pk_add_f32 v[86:87], v[86:87], 1.0 op_sel_hi:[1,0]
	v_rcp_f32_e32 v88, v88
	v_rcp_f32_e32 v89, v89
	v_rcp_f32_e32 v94, v94
	v_rcp_f32_e32 v95, v95
	v_rcp_f32_e32 v86, v86
	v_rcp_f32_e32 v87, v87
	v_mul_f32_e32 v100, v104, v104
	v_pk_mul_f32 v[90:91], v[90:91], v[100:101] op_sel_hi:[1,0]
	v_pk_mul_f32 v[92:93], v[92:93], v[100:101] op_sel_hi:[1,0]
	v_pk_mul_f32 v[84:85], v[84:85], v[100:101] op_sel_hi:[1,0]
	v_pk_add_f32 v[96:97], v[96:97], 1.0 op_sel_hi:[1,0]
	v_pk_mul_f32 v[88:89], v[90:91], v[88:89]
	v_rcp_f32_e32 v96, v96
	v_rcp_f32_e32 v97, v97
	v_pk_mul_f32 v[90:91], v[92:93], v[94:95]
	v_pk_mul_f32 v[86:87], v[84:85], v[86:87]
	v_or_b32_e32 v94, 32, v141
	v_cvt_pk_bf16_f32 v85, v86, v87
	v_mad_i64_i32 v[86:87], s[16:17], v94, s7, v[114:115]
	v_lshl_add_u64 v[86:87], v[86:87], 0, s[14:15]
	v_pk_mul_f32 v[82:83], v[82:83], v[100:101] op_sel_hi:[1,0]
	v_lshl_add_u64 v[86:87], v[86:87], 0, s[96:97]
	v_pk_mul_f32 v[92:93], v[82:83], v[96:97]
	v_cvt_pk_bf16_f32 v82, v88, v89
	v_lshl_add_u64 v[86:87], v[86:87], 0, v[190:191]
	v_cvt_pk_bf16_f32 v83, v90, v91
	v_cvt_pk_bf16_f32 v84, v92, v93
	global_store_dwordx4 v[86:87], v[82:85], off
	v_pk_mul_f32 v[76:77], v[80:81], v[76:77]
	v_pk_mul_f32 v[74:75], v[78:79], v[74:75]
	v_mul_f32_e32 v82, 0xbfb8aa3b, v105
	v_pk_mul_f32 v[86:87], v[78:79], v[82:83] op_sel_hi:[1,0]
	v_pk_mul_f32 v[78:79], v[80:81], v[82:83] op_sel_hi:[1,0]
	v_exp_f32_e32 v86, v86
	v_exp_f32_e32 v87, v87
	v_pk_mul_f32 v[80:81], v[70:71], v[82:83] op_sel_hi:[1,0]
	v_pk_mul_f32 v[66:67], v[70:71], v[66:67]
	v_pk_mul_f32 v[70:71], v[72:73], v[82:83] op_sel_hi:[1,0]
	v_exp_f32_e32 v78, v78
	v_exp_f32_e32 v79, v79
	v_exp_f32_e32 v80, v80
	v_exp_f32_e32 v81, v81
	v_exp_f32_e32 v70, v70
	v_exp_f32_e32 v71, v71
	v_pk_mul_f32 v[68:69], v[72:73], v[68:69]
	v_pk_add_f32 v[72:73], v[86:87], 1.0 op_sel_hi:[1,0]
	v_pk_add_f32 v[78:79], v[78:79], 1.0 op_sel_hi:[1,0]
	v_rcp_f32_e32 v72, v72
	v_rcp_f32_e32 v73, v73
	v_pk_add_f32 v[80:81], v[80:81], 1.0 op_sel_hi:[1,0]
	v_pk_add_f32 v[70:71], v[70:71], 1.0 op_sel_hi:[1,0]
	v_rcp_f32_e32 v78, v78
	v_rcp_f32_e32 v79, v79
	v_rcp_f32_e32 v80, v80
	v_rcp_f32_e32 v81, v81
	v_rcp_f32_e32 v70, v70
	v_rcp_f32_e32 v71, v71
	v_mul_f32_e32 v84, v105, v105
	v_pk_mul_f32 v[74:75], v[74:75], v[84:85] op_sel_hi:[1,0]
	v_pk_mul_f32 v[76:77], v[76:77], v[84:85] op_sel_hi:[1,0]
	v_pk_mul_f32 v[66:67], v[66:67], v[84:85] op_sel_hi:[1,0]
	v_pk_mul_f32 v[68:69], v[68:69], v[84:85] op_sel_hi:[1,0]
	v_pk_mul_f32 v[72:73], v[74:75], v[72:73]
	v_pk_mul_f32 v[74:75], v[76:77], v[78:79]
	v_pk_mul_f32 v[76:77], v[66:67], v[80:81]
	v_pk_mul_f32 v[70:71], v[68:69], v[70:71]
	v_or_b32_e32 v78, 48, v141
	v_cvt_pk_bf16_f32 v66, v72, v73
	ds_read2_b32 v[72:73], v142 offset0:128 offset1:144
	v_cvt_pk_bf16_f32 v69, v70, v71
	v_mad_i64_i32 v[70:71], s[16:17], v78, s7, v[114:115]
	v_lshl_add_u64 v[70:71], v[70:71], 0, s[14:15]
	v_lshl_add_u64 v[70:71], v[70:71], 0, s[96:97]
	v_cvt_pk_bf16_f32 v67, v74, v75
	v_lshl_add_u64 v[70:71], v[70:71], 0, v[190:191]
	v_cvt_pk_bf16_f32 v68, v76, v77
	global_store_dwordx4 v[70:71], v[66:69], off
	v_pk_mul_f32 v[60:61], v[64:65], v[60:61]
	v_pk_mul_f32 v[58:59], v[62:63], v[58:59]
	v_add_u32_e32 v67, 0x80, v141
	s_waitcnt lgkmcnt(0)
	v_mul_f32_e32 v66, 0xbfb8aa3b, v72
	v_pk_mul_f32 v[70:71], v[62:63], v[66:67] op_sel_hi:[1,0]
	v_pk_mul_f32 v[62:63], v[64:65], v[66:67] op_sel_hi:[1,0]
	v_pk_mul_f32 v[64:65], v[54:55], v[66:67] op_sel_hi:[1,0]
	v_pk_mul_f32 v[50:51], v[54:55], v[50:51]
	v_pk_mul_f32 v[54:55], v[56:57], v[66:67] op_sel_hi:[1,0]
	v_exp_f32_e32 v70, v70
	v_exp_f32_e32 v54, v54
	v_exp_f32_e32 v55, v55
	v_exp_f32_e32 v71, v71
	v_exp_f32_e32 v62, v62
	v_exp_f32_e32 v63, v63
	v_exp_f32_e32 v64, v64
	v_exp_f32_e32 v65, v65
	v_pk_add_f32 v[54:55], v[54:55], 1.0 op_sel_hi:[1,0]
	v_mul_f32_e32 v68, v72, v72
	v_rcp_f32_e32 v54, v54
	v_rcp_f32_e32 v55, v55
	v_pk_mul_f32 v[52:53], v[56:57], v[52:53]
	v_pk_add_f32 v[56:57], v[70:71], 1.0 op_sel_hi:[1,0]
	v_pk_mul_f32 v[52:53], v[52:53], v[68:69] op_sel_hi:[1,0]
	v_pk_add_f32 v[62:63], v[62:63], 1.0 op_sel_hi:[1,0]
	v_pk_add_f32 v[64:65], v[64:65], 1.0 op_sel_hi:[1,0]
	v_rcp_f32_e32 v56, v56
	v_rcp_f32_e32 v57, v57
	v_rcp_f32_e32 v62, v62
	v_rcp_f32_e32 v63, v63
	v_rcp_f32_e32 v64, v64
	v_rcp_f32_e32 v65, v65
	v_pk_mul_f32 v[54:55], v[52:53], v[54:55]
	v_pk_mul_f32 v[58:59], v[58:59], v[68:69] op_sel_hi:[1,0]
	v_cvt_pk_bf16_f32 v53, v54, v55
	v_mad_i64_i32 v[54:55], s[16:17], v67, s7, v[114:115]
	v_lshl_add_u64 v[54:55], v[54:55], 0, s[14:15]
	v_pk_mul_f32 v[60:61], v[60:61], v[68:69] op_sel_hi:[1,0]
	v_pk_mul_f32 v[50:51], v[50:51], v[68:69] op_sel_hi:[1,0]
	v_lshl_add_u64 v[54:55], v[54:55], 0, s[96:97]
	v_pk_mul_f32 v[56:57], v[58:59], v[56:57]
	v_pk_mul_f32 v[58:59], v[60:61], v[62:63]
	v_pk_mul_f32 v[60:61], v[50:51], v[64:65]
	v_cvt_pk_bf16_f32 v50, v56, v57
	v_lshl_add_u64 v[54:55], v[54:55], 0, v[190:191]
	v_cvt_pk_bf16_f32 v51, v58, v59
	v_cvt_pk_bf16_f32 v52, v60, v61
	global_store_dwordx4 v[54:55], v[50:53], off
	v_pk_mul_f32 v[44:45], v[48:49], v[44:45]
	v_pk_mul_f32 v[42:43], v[46:47], v[42:43]
	v_mul_f32_e32 v50, 0xbfb8aa3b, v73
	v_pk_mul_f32 v[54:55], v[46:47], v[50:51] op_sel_hi:[1,0]
	v_pk_mul_f32 v[46:47], v[48:49], v[50:51] op_sel_hi:[1,0]
	v_exp_f32_e32 v54, v54
	v_exp_f32_e32 v55, v55
	v_pk_mul_f32 v[48:49], v[38:39], v[50:51] op_sel_hi:[1,0]
	v_pk_mul_f32 v[34:35], v[38:39], v[34:35]
	v_pk_mul_f32 v[38:39], v[40:41], v[50:51] op_sel_hi:[1,0]
	v_exp_f32_e32 v46, v46
	v_exp_f32_e32 v47, v47
	v_exp_f32_e32 v48, v48
	v_exp_f32_e32 v49, v49
	v_exp_f32_e32 v38, v38
	v_exp_f32_e32 v39, v39
	v_pk_mul_f32 v[36:37], v[40:41], v[36:37]
	v_pk_add_f32 v[40:41], v[54:55], 1.0 op_sel_hi:[1,0]
	v_pk_add_f32 v[46:47], v[46:47], 1.0 op_sel_hi:[1,0]
	v_rcp_f32_e32 v40, v40
	v_rcp_f32_e32 v41, v41
	v_pk_add_f32 v[48:49], v[48:49], 1.0 op_sel_hi:[1,0]
	v_pk_add_f32 v[38:39], v[38:39], 1.0 op_sel_hi:[1,0]
	v_rcp_f32_e32 v46, v46
	v_rcp_f32_e32 v47, v47
	v_rcp_f32_e32 v48, v48
	v_rcp_f32_e32 v49, v49
	v_rcp_f32_e32 v38, v38
	v_rcp_f32_e32 v39, v39
	v_mul_f32_e32 v52, v73, v73
	v_pk_mul_f32 v[42:43], v[42:43], v[52:53] op_sel_hi:[1,0]
	v_pk_mul_f32 v[44:45], v[44:45], v[52:53] op_sel_hi:[1,0]
	v_pk_mul_f32 v[34:35], v[34:35], v[52:53] op_sel_hi:[1,0]
	v_pk_mul_f32 v[36:37], v[36:37], v[52:53] op_sel_hi:[1,0]
	v_pk_mul_f32 v[40:41], v[42:43], v[40:41]
	v_pk_mul_f32 v[42:43], v[44:45], v[46:47]
	v_pk_mul_f32 v[44:45], v[34:35], v[48:49]
	v_pk_mul_f32 v[38:39], v[36:37], v[38:39]
	v_add_u32_e32 v46, 0x90, v141
	v_cvt_pk_bf16_f32 v34, v40, v41
	ds_read2_b32 v[40:41], v142 offset0:160 offset1:176
	v_cvt_pk_bf16_f32 v37, v38, v39
	v_mad_i64_i32 v[38:39], s[16:17], v46, s7, v[114:115]
	v_lshl_add_u64 v[38:39], v[38:39], 0, s[14:15]
	v_lshl_add_u64 v[38:39], v[38:39], 0, s[96:97]
	v_lshl_add_u64 v[38:39], v[38:39], 0, v[190:191]
	v_cvt_pk_bf16_f32 v35, v42, v43
	v_cvt_pk_bf16_f32 v36, v44, v45
	global_store_dwordx4 v[38:39], v[34:37], off
	v_pk_mul_f32 v[28:29], v[32:33], v[28:29]
	v_pk_mul_f32 v[26:27], v[30:31], v[26:27]
	s_waitcnt lgkmcnt(0)
	v_mul_f32_e32 v34, 0xbfb8aa3b, v40
	v_pk_mul_f32 v[38:39], v[30:31], v[34:35] op_sel_hi:[1,0]
	v_pk_mul_f32 v[30:31], v[32:33], v[34:35] op_sel_hi:[1,0]
	v_pk_mul_f32 v[32:33], v[22:23], v[34:35] op_sel_hi:[1,0]
	v_pk_mul_f32 v[18:19], v[22:23], v[18:19]
	v_pk_mul_f32 v[22:23], v[24:25], v[34:35] op_sel_hi:[1,0]
	v_exp_f32_e32 v38, v38
	v_exp_f32_e32 v39, v39
	v_exp_f32_e32 v30, v30
	v_exp_f32_e32 v31, v31
	v_exp_f32_e32 v22, v22
	v_exp_f32_e32 v23, v23
	v_exp_f32_e32 v32, v32
	v_exp_f32_e32 v33, v33
	v_pk_mul_f32 v[20:21], v[24:25], v[20:21]
	v_pk_add_f32 v[24:25], v[38:39], 1.0 op_sel_hi:[1,0]
	v_pk_add_f32 v[30:31], v[30:31], 1.0 op_sel_hi:[1,0]
	v_pk_add_f32 v[22:23], v[22:23], 1.0 op_sel_hi:[1,0]
	v_rcp_f32_e32 v24, v24
	v_rcp_f32_e32 v25, v25
	v_rcp_f32_e32 v30, v30
	v_rcp_f32_e32 v31, v31
	v_rcp_f32_e32 v22, v22
	v_rcp_f32_e32 v23, v23
	v_mul_f32_e32 v36, v40, v40
	v_pk_mul_f32 v[26:27], v[26:27], v[36:37] op_sel_hi:[1,0]
	v_pk_mul_f32 v[28:29], v[28:29], v[36:37] op_sel_hi:[1,0]
	v_pk_mul_f32 v[20:21], v[20:21], v[36:37] op_sel_hi:[1,0]
	v_pk_add_f32 v[32:33], v[32:33], 1.0 op_sel_hi:[1,0]
	v_pk_mul_f32 v[24:25], v[26:27], v[24:25]
	v_rcp_f32_e32 v32, v32
	v_rcp_f32_e32 v33, v33
	v_pk_mul_f32 v[26:27], v[28:29], v[30:31]
	v_pk_mul_f32 v[22:23], v[20:21], v[22:23]
	v_add_u32_e32 v30, 0xa0, v141
	v_cvt_pk_bf16_f32 v21, v22, v23
	v_mad_i64_i32 v[22:23], s[16:17], v30, s7, v[114:115]
	v_lshl_add_u64 v[22:23], v[22:23], 0, s[14:15]
	v_pk_mul_f32 v[18:19], v[18:19], v[36:37] op_sel_hi:[1,0]
	v_lshl_add_u64 v[22:23], v[22:23], 0, s[96:97]
	v_pk_mul_f32 v[28:29], v[18:19], v[32:33]
	v_cvt_pk_bf16_f32 v18, v24, v25
	v_lshl_add_u64 v[22:23], v[22:23], 0, v[190:191]
	v_cvt_pk_bf16_f32 v19, v26, v27
	v_cvt_pk_bf16_f32 v20, v28, v29
	global_store_dwordx4 v[22:23], v[18:21], off
	v_pk_mul_f32 v[12:13], v[16:17], v[12:13]
	v_pk_mul_f32 v[10:11], v[14:15], v[10:11]
	v_mul_f32_e32 v18, 0xbfb8aa3b, v41
	v_pk_mul_f32 v[22:23], v[14:15], v[18:19] op_sel_hi:[1,0]
	v_pk_mul_f32 v[14:15], v[16:17], v[18:19] op_sel_hi:[1,0]
	v_pk_mul_f32 v[16:17], v[6:7], v[18:19] op_sel_hi:[1,0]
	v_pk_mul_f32 v[2:3], v[6:7], v[2:3]
	v_pk_mul_f32 v[6:7], v[8:9], v[18:19] op_sel_hi:[1,0]
	v_exp_f32_e32 v22, v22
	v_exp_f32_e32 v23, v23
	v_exp_f32_e32 v14, v14
	v_exp_f32_e32 v15, v15
	v_exp_f32_e32 v6, v6
	v_exp_f32_e32 v7, v7
	v_pk_mul_f32 v[4:5], v[8:9], v[4:5]
	v_pk_add_f32 v[8:9], v[22:23], 1.0 op_sel_hi:[1,0]
	v_pk_add_f32 v[14:15], v[14:15], 1.0 op_sel_hi:[1,0]
	v_pk_add_f32 v[6:7], v[6:7], 1.0 op_sel_hi:[1,0]
	v_exp_f32_e32 v16, v16
	v_exp_f32_e32 v17, v17
	v_rcp_f32_e32 v8, v8
	v_rcp_f32_e32 v9, v9
	v_rcp_f32_e32 v14, v14
	v_rcp_f32_e32 v15, v15
	v_rcp_f32_e32 v6, v6
	v_rcp_f32_e32 v7, v7
	v_mul_f32_e32 v20, v41, v41
	v_pk_mul_f32 v[10:11], v[10:11], v[20:21] op_sel_hi:[1,0]
	v_pk_mul_f32 v[12:13], v[12:13], v[20:21] op_sel_hi:[1,0]
	v_pk_mul_f32 v[4:5], v[4:5], v[20:21] op_sel_hi:[1,0]
	v_pk_add_f32 v[16:17], v[16:17], 1.0 op_sel_hi:[1,0]
	v_pk_mul_f32 v[8:9], v[10:11], v[8:9]
	v_pk_mul_f32 v[10:11], v[12:13], v[14:15]
	v_pk_mul_f32 v[6:7], v[4:5], v[6:7]
	v_add_u32_e32 v14, 0xb0, v141
	v_rcp_f32_e32 v16, v16
	v_rcp_f32_e32 v17, v17
	v_cvt_pk_bf16_f32 v5, v6, v7
	v_mad_i64_i32 v[6:7], s[16:17], v14, s7, v[114:115]
	v_lshl_add_u64 v[6:7], v[6:7], 0, s[14:15]
	v_lshl_add_u64 v[6:7], v[6:7], 0, s[96:97]
	v_pk_mul_f32 v[2:3], v[2:3], v[20:21] op_sel_hi:[1,0]
	v_lshl_add_u64 v[6:7], v[6:7], 0, v[190:191]
	s_and_b64 vcc, exec, s[38:39]
	s_mov_b32 s35, s6
	s_mov_b32 s36, s8
	s_mov_b64 s[16:17], s[12:13]
	s_mov_b64 s[14:15], s[10:11]
	s_mov_b32 s37, s34
	v_pk_mul_f32 v[12:13], v[2:3], v[16:17]
	v_cvt_pk_bf16_f32 v2, v8, v9
	v_cvt_pk_bf16_f32 v3, v10, v11
	s_nop 0
	v_cvt_pk_bf16_f32 v4, v12, v13
	global_store_dwordx4 v[6:7], v[2:5], off
	s_cbranch_vccz .LBB0_92
	s_waitcnt vmcnt(0)
	v_readlane_b32 s30, v252, 21
	s_cmpk_gt_u32 s22, 0xff
	v_readlane_b32 s31, v252, 22
	s_mov_b32 s34, 0x800000
	s_movk_i32 s35, 0x4000
	s_movk_i32 s36, 0x90
	s_movk_i32 s37, 0x300
	s_movk_i32 s54, 0x2810
	s_movk_i32 s55, 0xdff
	v_readlane_b32 s56, v252, 31
	s_movk_i32 s57, 0x110
	s_mov_b32 s58, 0x2aaaaaab
	s_movk_i32 s59, 0xffd0
	v_readlane_b32 s76, v252, 46
	s_cbranch_scc1 .LBB0_103
	s_barrier

.LBB0_450:
	s_or_b64 exec, exec, s[0:1]
	s_mov_b64 s[0:1], src_shared_base
	s_add_i32 s0, 0, 0x20008
	s_cmp_lg_u32 s0, -1
	s_cselect_b32 s0, s0, 0
	s_cselect_b32 s1, s1, 0
	v_mov_b32_e32 v2, s0
	v_mov_b32_e32 v3, s1
	s_waitcnt lgkmcnt(0)
	s_barrier
	flat_load_dword v159, v[2:3] sc0 sc1
	s_waitcnt vmcnt(0)
	v_readlane_b32 s0, v255, 63
	s_cmp_eq_u32 s0, 0
	s_cselect_b32 s0, 1440, 0
	v_readlane_b32 s1, v252, 46
	s_cmp_eq_u32 s1, 3
	s_cselect_b32 s0, s0, 0
	v_subrev_u32_e32 v159, s0, v159
	s_cmp_lg_u32 s0, 0
	s_cbranch_scc0 .Lq_norm
	v_add_u32_e32 v159, 32, v159
	v_cmp_lt_i32_e32 vcc, 607, v159
	v_mov_b32_e32 v2, 0x7fffffff
	s_nop 1
	v_cndmask_b32_e32 v159, v159, v2, vcc
.Lq_norm:
	s_movk_i32 s0, 0x4a0
	s_waitcnt lgkmcnt(0)
	v_cmp_gt_i32_e32 vcc, s0, v159
	s_movk_i32 s0, 0x49f
	v_cmp_lt_i32_e64 s[0:1], s0, v159
	s_nop 1
	v_writelane_b32 v254, s0, 16
	s_nop 1
	v_writelane_b32 v254, s1, 17
	s_mov_b64 s[0:1], exec
	v_writelane_b32 v254, s0, 18
	s_nop 1
	v_writelane_b32 v254, s1, 19
	s_and_b64 s[0:1], s[0:1], vcc
	s_mov_b64 exec, s[0:1]
	s_cbranch_execz .LBB0_447
	s_and_saveexec_b64 s[0:1], s[34:35]
	s_cbranch_execz .LBB0_455
	s_mov_b64 s[4:5], exec
	v_mbcnt_lo_u32_b32 v2, s4, 0
	v_mbcnt_hi_u32_b32 v2, s5, v2
	v_cmp_eq_u32_e32 vcc, 0, v2
	s_and_saveexec_b64 s[2:3], vcc
	s_cbranch_execz .LBB0_454
	s_bcnt1_i32_b64 s4, s[4:5]
	v_mov_b32_e32 v3, s4
	global_atomic_add v3, v191, v3, s[28:29] sc0

.LBB0_628:
	s_or_b64 exec, exec, s[0:1]
	s_waitcnt lgkmcnt(0)
	s_barrier
	v_readlane_b32 s98, v255, 63
	v_readlane_b32 s99, v252, 46
	s_cmp_eq_u32 s98, 0
	s_cselect_b32 s98, 1, 0
	s_cmp_eq_u32 s99, 3
	s_cselect_b32 s98, s98, 0
	s_cmp_lg_u32 s98, 0
	s_cbranch_scc1 .LBB0_631
	s_and_saveexec_b64 s[0:1], s[42:43]
	s_cbranch_execz .LBB0_630
	v_lshlrev_b32_e32 v2, 6, v60
	v_or3_b32 v2, v2, v59, v57
	v_lshl_add_u32 v6, v65, 1, 0
	s_movk_i32 s6, 0x190
	v_mad_u64_u32 v[26:27], s[4:5], v2, s6, v[6:7]
	ds_read_b128 v[2:5], v26 offset:53248
	v_mad_u32_u24 v27, v57, s6, v6
	ds_read_b128 v[6:9], v27 offset:27648
	ds_read_b128 v[10:13], v27 offset:34048
	ds_read_b128 v[14:17], v27 offset:40448
	ds_read_b128 v[18:21], v27 offset:46848
	s_waitcnt lgkmcnt(3)
	v_mfma_f32_16x16x32_bf16 v[6:9], v[2:5], v[6:9], 0
	v_readlane_b32 s4, v251, 44
	s_mov_b64 s[6:7], 0xd495200
	s_waitcnt lgkmcnt(2)
	v_mfma_f32_16x16x32_bf16 v[10:13], v[2:5], v[10:13], 0
	s_waitcnt lgkmcnt(1)
	v_mfma_f32_16x16x32_bf16 v[14:17], v[2:5], v[14:17], 0
	s_waitcnt lgkmcnt(0)
	v_mfma_f32_16x16x32_bf16 v[2:5], v[2:5], v[18:21], 0
	ds_read_b128 v[18:21], v26 offset:53312
	ds_read_b128 v[22:25], v27 offset:27712
	s_waitcnt lgkmcnt(0)
	v_mfma_f32_16x16x32_bf16 v[6:9], v[18:21], v[22:25], v[6:9]
	ds_read_b128 v[22:25], v27 offset:34112
	s_waitcnt lgkmcnt(0)
	v_mfma_f32_16x16x32_bf16 v[10:13], v[18:21], v[22:25], v[10:13]
	ds_read_b128 v[22:25], v27 offset:40512
	s_waitcnt lgkmcnt(0)
	v_mfma_f32_16x16x32_bf16 v[14:17], v[18:21], v[22:25], v[14:17]
	ds_read_b128 v[22:25], v27 offset:46912
	s_waitcnt lgkmcnt(0)
	v_mfma_f32_16x16x32_bf16 v[2:5], v[18:21], v[22:25], v[2:5]
	ds_read_b128 v[18:21], v26 offset:53376
	ds_read_b128 v[22:25], v27 offset:27776
	s_waitcnt lgkmcnt(0)
	v_mfma_f32_16x16x32_bf16 v[6:9], v[18:21], v[22:25], v[6:9]
	ds_read_b128 v[22:25], v27 offset:34176
	s_waitcnt lgkmcnt(0)
	v_mfma_f32_16x16x32_bf16 v[10:13], v[18:21], v[22:25], v[10:13]
	ds_read_b128 v[22:25], v27 offset:40576
	s_waitcnt lgkmcnt(0)
	v_mfma_f32_16x16x32_bf16 v[14:17], v[18:21], v[22:25], v[14:17]
	ds_read_b128 v[22:25], v27 offset:46976
	s_waitcnt lgkmcnt(0)
	v_mfma_f32_16x16x32_bf16 v[2:5], v[18:21], v[22:25], v[2:5]
	ds_read_b128 v[18:21], v26 offset:53440
	ds_read_b128 v[22:25], v27 offset:27840
	s_waitcnt lgkmcnt(0)
	v_mfma_f32_16x16x32_bf16 v[6:9], v[18:21], v[22:25], v[6:9]
	ds_read_b128 v[22:25], v27 offset:34240
	s_waitcnt lgkmcnt(0)
	v_mfma_f32_16x16x32_bf16 v[10:13], v[18:21], v[22:25], v[10:13]
	ds_read_b128 v[22:25], v27 offset:40640
	s_waitcnt lgkmcnt(0)
	v_mfma_f32_16x16x32_bf16 v[14:17], v[18:21], v[22:25], v[14:17]
	ds_read_b128 v[22:25], v27 offset:47040
	s_waitcnt lgkmcnt(0)
	v_mfma_f32_16x16x32_bf16 v[2:5], v[18:21], v[22:25], v[2:5]
	ds_read_b128 v[18:21], v26 offset:53504
	ds_read_b128 v[22:25], v27 offset:27904
	s_waitcnt lgkmcnt(0)
	v_mfma_f32_16x16x32_bf16 v[6:9], v[18:21], v[22:25], v[6:9]
	ds_read_b128 v[22:25], v27 offset:34304
	s_waitcnt lgkmcnt(0)
	v_mfma_f32_16x16x32_bf16 v[10:13], v[18:21], v[22:25], v[10:13]
	ds_read_b128 v[22:25], v27 offset:40704
	s_waitcnt lgkmcnt(0)
	v_mfma_f32_16x16x32_bf16 v[14:17], v[18:21], v[22:25], v[14:17]
	ds_read_b128 v[22:25], v27 offset:47104
	s_waitcnt lgkmcnt(0)
	v_mfma_f32_16x16x32_bf16 v[18:21], v[18:21], v[22:25], v[2:5]
	ds_read_b128 v[22:25], v26 offset:53568
	s_nop 1
	ds_read_b128 v[2:5], v27 offset:27968
	s_waitcnt lgkmcnt(0)
	v_mfma_f32_16x16x32_bf16 v[2:5], v[22:25], v[2:5], v[6:9]
	s_nop 2
	ds_read_b128 v[6:9], v27 offset:34368
	s_waitcnt lgkmcnt(0)
	v_mfma_f32_16x16x32_bf16 v[6:9], v[22:25], v[6:9], v[10:13]
	s_nop 2
	ds_read_b128 v[10:13], v27 offset:40768
	s_waitcnt lgkmcnt(0)
	v_mfma_f32_16x16x32_bf16 v[10:13], v[22:25], v[10:13], v[14:17]
	s_nop 2
	ds_read_b128 v[14:17], v27 offset:47168
	s_waitcnt lgkmcnt(0)
	v_mfma_f32_16x16x32_bf16 v[14:17], v[22:25], v[14:17], v[18:21]
	s_nop 2
	v_lshlrev_b32_e32 v19, 2, v64
	v_lshl_or_b32 v18, v58, 2, v59
	v_add3_u32 v28, s4, v19, v190
	v_add_u32_e32 v190, v56, v18
	ds_read2_b32 v[18:19], v28 offset1:1
	v_lshlrev_b64 v[20:21], 11, v[190:191]
	v_lshl_add_u64 v[20:21], s[72:73], 0, v[20:21]
	v_lshlrev_b64 v[22:23], 1, v[54:55]
	v_lshl_add_u64 v[20:21], v[20:21], 0, v[22:23]
	v_lshlrev_b32_e32 v24, 1, v57
	v_mov_b32_e32 v25, v191
	v_lshl_add_u64 v[20:21], v[20:21], 0, v[24:25]
	s_mov_b32 s4, 0xd495000
	v_lshl_add_u64 v[26:27], v[20:21], 0, s[6:7]
	s_waitcnt lgkmcnt(0)
	v_mul_f32_e32 v2, v2, v18
	v_add_co_u32_e32 v20, vcc, s4, v20
	v_cvt_pk_bf16_f32 v2, v2, v191
	ds_read2_b32 v[28:29], v28 offset0:2 offset1:3
	s_nop 0
	v_addc_co_u32_e32 v21, vcc, 0, v21, vcc
	global_store_short v[20:21], v2, off offset:512
	v_mul_f32_e32 v2, v6, v18
	v_cvt_pk_bf16_f32 v2, v2, v191
	global_store_short v[26:27], v2, off offset:32
	v_mul_f32_e32 v2, v10, v18
	v_add_u32_e32 v20, 1, v190
	v_mov_b32_e32 v21, v191
	v_cvt_pk_bf16_f32 v2, v2, v191
	v_lshlrev_b64 v[20:21], 11, v[20:21]
	global_store_short v[26:27], v2, off offset:64
	v_mul_f32_e32 v2, v18, v14
	v_lshl_add_u64 v[20:21], s[72:73], 0, v[20:21]
	v_cvt_pk_bf16_f32 v2, v2, v191
	v_lshl_add_u64 v[20:21], v[20:21], 0, v[22:23]
	global_store_short v[26:27], v2, off offset:96
	v_lshl_add_u64 v[20:21], v[20:21], 0, v[24:25]
	v_mul_f32_e32 v2, v3, v19
	v_cvt_pk_bf16_f32 v6, v2, v191
	v_add_co_u32_e32 v2, vcc, s4, v20
	v_lshl_add_u64 v[26:27], v[20:21], 0, s[6:7]
	s_nop 0
	v_addc_co_u32_e32 v3, vcc, 0, v21, vcc
	global_store_short v[2:3], v6, off offset:512
	v_mul_f32_e32 v2, v7, v19
	v_cvt_pk_bf16_f32 v2, v2, v191
	global_store_short v[26:27], v2, off offset:32
	v_mul_f32_e32 v2, v11, v19
	v_cvt_pk_bf16_f32 v2, v2, v191
	global_store_short v[26:27], v2, off offset:64
	v_mul_f32_e32 v2, v15, v19
	v_cvt_pk_bf16_f32 v2, v2, v191
	global_store_short v[26:27], v2, off offset:96
	v_add_u32_e32 v2, 2, v190
	v_mov_b32_e32 v3, v191
	v_lshlrev_b64 v[2:3], 11, v[2:3]
	v_lshl_add_u64 v[2:3], s[72:73], 0, v[2:3]
	v_lshl_add_u64 v[2:3], v[2:3], 0, v[22:23]
	v_lshl_add_u64 v[2:3], v[2:3], 0, v[24:25]
	v_lshl_add_u64 v[6:7], v[2:3], 0, s[6:7]
	v_add_co_u32_e32 v2, vcc, s4, v2
	s_waitcnt lgkmcnt(0)
	v_mul_f32_e32 v4, v4, v28
	v_addc_co_u32_e32 v3, vcc, 0, v3, vcc
	v_cvt_pk_bf16_f32 v4, v4, v191
	global_store_short v[2:3], v4, off offset:512
	v_mul_f32_e32 v2, v8, v28
	v_cvt_pk_bf16_f32 v2, v2, v191
	global_store_short v[6:7], v2, off offset:32
	v_mul_f32_e32 v2, v12, v28
	v_cvt_pk_bf16_f32 v2, v2, v191
	global_store_short v[6:7], v2, off offset:64
	v_mul_f32_e32 v2, v16, v28
	v_cvt_pk_bf16_f32 v2, v2, v191
	v_add_u32_e32 v190, 3, v190
	global_store_short v[6:7], v2, off offset:96
	v_lshlrev_b64 v[2:3], 11, v[190:191]
	v_lshl_add_u64 v[2:3], s[72:73], 0, v[2:3]
	v_lshl_add_u64 v[2:3], v[2:3], 0, v[22:23]
	v_lshl_add_u64 v[2:3], v[2:3], 0, v[24:25]
	v_lshl_add_u64 v[6:7], v[2:3], 0, s[6:7]
	v_add_co_u32_e32 v2, vcc, s4, v2
	v_mul_f32_e32 v4, v5, v29
	s_nop 0
	v_addc_co_u32_e32 v3, vcc, 0, v3, vcc
	v_cvt_pk_bf16_f32 v4, v4, v191
	global_store_short v[2:3], v4, off offset:512
	v_mul_f32_e32 v2, v9, v29
	v_cvt_pk_bf16_f32 v2, v2, v191
	global_store_short v[6:7], v2, off offset:32
	v_mul_f32_e32 v2, v13, v29
	v_cvt_pk_bf16_f32 v2, v2, v191
	global_store_short v[6:7], v2, off offset:64
	v_mul_f32_e32 v2, v17, v29
	v_cvt_pk_bf16_f32 v2, v2, v191
	global_store_short v[6:7], v2, off offset:96
